# attention: second-half softmax spread over 12 PV MFMA gaps in each step's first sub-tile (on top of v106)
# baseline (speedup 1.0000x reference)
.Lnd_107:
	s_and_b32 s33, s42, 1
	s_mul_i32 s6, s33, 0x9000
	v_add_u32_e32 v199, s6, v187
	v_add_u32_e32 v198, s6, v188
	s_mov_b64 s[54:55], exec
	v_readfirstlane_b32 s4, v186
	s_bitcmp1_b32 s4, 8
	s_cbranch_scc1 .Lab_B
	ds_read_b128 v[216:219], v199 offset:0
	ds_read_b128 v[232:235], v193 offset:0
	ds_read_b128 v[220:223], v199 offset:32
	ds_read_b128 v[236:239], v193 offset:32
	ds_read_b128 v[224:227], v199 offset:64
	ds_read_b128 v[244:247], v193 offset:64
	ds_read_b128 v[228:231], v199 offset:96
	ds_read_b128 v[248:251], v193 offset:96
	s_waitcnt lgkmcnt(6)
	v_mfma_f32_32x32x16_bf16 v[144:159], v[216:219], v[232:235], v[0:15]
	s_waitcnt lgkmcnt(4)
	v_mfma_f32_32x32x16_bf16 v[144:159], v[220:223], v[236:239], v[144:159]
	s_waitcnt lgkmcnt(2)
	v_mfma_f32_32x32x16_bf16 v[144:159], v[224:227], v[244:247], v[144:159]
	s_waitcnt lgkmcnt(0)
	v_mfma_f32_32x32x16_bf16 v[144:159], v[228:231], v[248:251], v[144:159]
	ds_read_b128 v[216:219], v199 offset:9216
	ds_read_b128 v[232:235], v193 offset:36864
	ds_read_b128 v[220:223], v199 offset:9248
	ds_read_b128 v[236:239], v193 offset:36896
	ds_read_b128 v[224:227], v199 offset:9280
	ds_read_b128 v[244:247], v193 offset:36928
	ds_read_b128 v[228:231], v199 offset:9312
	ds_read_b128 v[248:251], v193 offset:36960
	s_nop 3
	v_exp_f32_e32 v144, v144
	v_exp_f32_e32 v145, v145
	v_exp_f32_e32 v146, v146
	v_add_f32_e32 v243, v144, v145
	v_exp_f32_e32 v147, v147
	v_add_f32_e32 v243, v146, v243
	v_exp_f32_e32 v148, v148
	v_add_f32_e32 v243, v147, v243
	v_exp_f32_e32 v149, v149
	v_add_f32_e32 v243, v148, v243
	v_exp_f32_e32 v150, v150
	v_add_f32_e32 v243, v149, v243
	v_exp_f32_e32 v151, v151
	v_add_f32_e32 v243, v150, v243
	v_exp_f32_e32 v152, v152
	v_add_f32_e32 v243, v151, v243
	v_exp_f32_e32 v153, v153
	v_add_f32_e32 v243, v152, v243
	v_exp_f32_e32 v154, v154
	v_add_f32_e32 v243, v153, v243
	v_exp_f32_e32 v155, v155
	v_add_f32_e32 v243, v154, v243
	v_exp_f32_e32 v156, v156
	v_add_f32_e32 v243, v155, v243
	s_waitcnt lgkmcnt(6)
	v_mfma_f32_32x32x16_bf16 v[200:215], v[216:219], v[232:235], v[0:15]
	v_exp_f32_e32 v157, v157
	v_add_f32_e32 v243, v156, v243
	v_exp_f32_e32 v158, v158
	v_add_f32_e32 v243, v157, v243
	s_waitcnt lgkmcnt(4)
	v_mfma_f32_32x32x16_bf16 v[200:215], v[220:223], v[236:239], v[200:215]
	v_exp_f32_e32 v159, v159
	v_add_f32_e32 v243, v158, v243
	v_add_f32_e32 v243, v159, v243
	v_add_f32_e32 v196, v196, v243
	s_waitcnt lgkmcnt(2)
	v_mfma_f32_32x32x16_bf16 v[200:215], v[224:227], v[244:247], v[200:215]
	v_cvt_pk_bf16_f32 v144, v144, v145
	v_cvt_pk_bf16_f32 v145, v146, v147
	v_cvt_pk_bf16_f32 v146, v148, v149
	v_cvt_pk_bf16_f32 v147, v150, v151
	s_waitcnt lgkmcnt(0)
	v_mfma_f32_32x32x16_bf16 v[200:215], v[228:231], v[248:251], v[200:215]
	ds_read_b128 v[216:219], v198 offset:0
	ds_read_b128 v[224:227], v198 offset:4608
	ds_read_b128 v[232:235], v198 offset:9216
	ds_read_b128 v[244:247], v198 offset:13824
	ds_read_b128 v[220:223], v198 offset:32
	ds_read_b128 v[228:231], v198 offset:4640
	ds_read_b128 v[236:239], v198 offset:9248
	ds_read_b128 v[248:251], v198 offset:13856
	v_cvt_pk_bf16_f32 v148, v152, v153
	v_cvt_pk_bf16_f32 v149, v154, v155
	v_cvt_pk_bf16_f32 v150, v156, v157
	v_cvt_pk_bf16_f32 v151, v158, v159
	s_waitcnt lgkmcnt(7)
	v_mfma_f32_32x32x16_bf16 v[112:127], v[216:219], v[144:147], v[112:127]
	v_exp_f32_e32 v200, v200
	v_exp_f32_e32 v201, v201
	v_exp_f32_e32 v202, v202
	s_waitcnt lgkmcnt(6)
	v_mfma_f32_32x32x16_bf16 v[80:95], v[224:227], v[144:147], v[80:95]
	v_add_f32_e32 v243, v200, v201
	v_exp_f32_e32 v203, v203
	v_add_f32_e32 v243, v202, v243
	s_waitcnt lgkmcnt(5)
	v_mfma_f32_32x32x16_bf16 v[48:63], v[232:235], v[144:147], v[48:63]
	v_exp_f32_e32 v204, v204
	v_add_f32_e32 v243, v203, v243
	v_exp_f32_e32 v205, v205
	s_waitcnt lgkmcnt(4)
	v_mfma_f32_32x32x16_bf16 v[16:31], v[244:247], v[144:147], v[16:31]
	v_add_f32_e32 v243, v204, v243
	v_exp_f32_e32 v206, v206
	v_add_f32_e32 v243, v205, v243
	s_waitcnt lgkmcnt(3)
	v_mfma_f32_32x32x16_bf16 v[112:127], v[220:223], v[148:151], v[112:127]
	v_exp_f32_e32 v207, v207
	v_add_f32_e32 v243, v206, v243
	v_exp_f32_e32 v208, v208
	s_waitcnt lgkmcnt(2)
	v_mfma_f32_32x32x16_bf16 v[80:95], v[228:231], v[148:151], v[80:95]
	v_add_f32_e32 v243, v207, v243
	v_cvt_pk_bf16_f32 v200, v200, v201
	v_cvt_pk_bf16_f32 v201, v202, v203
	s_waitcnt lgkmcnt(1)
	v_mfma_f32_32x32x16_bf16 v[48:63], v[236:239], v[148:151], v[48:63]
	v_cvt_pk_bf16_f32 v202, v204, v205
	v_cvt_pk_bf16_f32 v203, v206, v207
	v_exp_f32_e32 v209, v209
	s_waitcnt lgkmcnt(0)
	v_mfma_f32_32x32x16_bf16 v[16:31], v[248:251], v[148:151], v[16:31]
	v_add_f32_e32 v243, v208, v243
	v_exp_f32_e32 v210, v210
	v_add_f32_e32 v243, v209, v243
	v_mfma_f32_32x32x16_bf16 v[128:143], v[216:219], v[200:203], v[128:143]
	v_exp_f32_e32 v211, v211
	v_add_f32_e32 v243, v210, v243
	v_exp_f32_e32 v212, v212
	v_add_f32_e32 v243, v211, v243
	v_mfma_f32_32x32x16_bf16 v[96:111], v[224:227], v[200:203], v[96:111]
	v_exp_f32_e32 v213, v213
	v_add_f32_e32 v243, v212, v243
	v_exp_f32_e32 v214, v214
	v_add_f32_e32 v243, v213, v243
	v_mfma_f32_32x32x16_bf16 v[64:79], v[232:235], v[200:203], v[64:79]
	v_exp_f32_e32 v215, v215
	v_add_f32_e32 v243, v214, v243
	v_add_f32_e32 v243, v215, v243
	v_add_f32_e32 v197, v197, v243
	v_mfma_f32_32x32x16_bf16 v[32:47], v[244:247], v[200:203], v[32:47]
	v_cvt_pk_bf16_f32 v204, v208, v209
	v_cvt_pk_bf16_f32 v205, v210, v211
	v_cvt_pk_bf16_f32 v206, v212, v213
	v_cvt_pk_bf16_f32 v207, v214, v215
	ds_read_b128 v[252:255], v199 offset:4608
	ds_read_b128 v[208:211], v193
	ds_read_b128 v[212:215], v199 offset:4640
	v_mfma_f32_32x32x16_bf16 v[128:143], v[220:223], v[204:207], v[128:143]
	v_mfma_f32_32x32x16_bf16 v[96:111], v[228:231], v[204:207], v[96:111]
	v_mfma_f32_32x32x16_bf16 v[64:79], v[236:239], v[204:207], v[64:79]
	v_mfma_f32_32x32x16_bf16 v[32:47], v[248:251], v[204:207], v[32:47]
	ds_read_b128 v[236:239], v193 offset:32
	ds_read_b128 v[224:227], v199 offset:4672
	ds_read_b128 v[244:247], v193 offset:64
	ds_read_b128 v[228:231], v199 offset:4704
	ds_read_b128 v[248:251], v193 offset:96
	s_waitcnt lgkmcnt(6)
	v_mfma_f32_32x32x16_bf16 v[144:159], v[252:255], v[208:211], v[0:15]
	s_waitcnt lgkmcnt(4)
	v_mfma_f32_32x32x16_bf16 v[144:159], v[212:215], v[236:239], v[144:159]
	s_waitcnt lgkmcnt(2)
	v_mfma_f32_32x32x16_bf16 v[144:159], v[224:227], v[244:247], v[144:159]
	s_waitcnt lgkmcnt(0)
	v_mfma_f32_32x32x16_bf16 v[144:159], v[228:231], v[248:251], v[144:159]
	ds_read_b128 v[216:219], v199 offset:13824
	ds_read_b128 v[232:235], v193 offset:36864
	ds_read_b128 v[220:223], v199 offset:13856
	ds_read_b128 v[236:239], v193 offset:36896
	ds_read_b128 v[224:227], v199 offset:13888
	ds_read_b128 v[244:247], v193 offset:36928
	ds_read_b128 v[228:231], v199 offset:13920
	ds_read_b128 v[248:251], v193 offset:36960
	s_nop 3
	v_exp_f32_e32 v144, v144
	v_exp_f32_e32 v145, v145
	v_exp_f32_e32 v146, v146
	v_add_f32_e32 v243, v144, v145
	v_exp_f32_e32 v147, v147
	v_add_f32_e32 v243, v146, v243
	v_exp_f32_e32 v148, v148
	v_add_f32_e32 v243, v147, v243
	v_exp_f32_e32 v149, v149
	v_add_f32_e32 v243, v148, v243
	v_exp_f32_e32 v150, v150
	v_add_f32_e32 v243, v149, v243
	v_exp_f32_e32 v151, v151
	v_add_f32_e32 v243, v150, v243
	v_exp_f32_e32 v152, v152
	v_add_f32_e32 v243, v151, v243
	v_exp_f32_e32 v153, v153
	v_add_f32_e32 v243, v152, v243
	v_exp_f32_e32 v154, v154
	v_add_f32_e32 v243, v153, v243
	v_exp_f32_e32 v155, v155
	v_add_f32_e32 v243, v154, v243
	v_exp_f32_e32 v156, v156
	v_add_f32_e32 v243, v155, v243
	s_waitcnt lgkmcnt(6)
	v_mfma_f32_32x32x16_bf16 v[200:215], v[216:219], v[232:235], v[0:15]
	v_exp_f32_e32 v157, v157
	v_add_f32_e32 v243, v156, v243
	v_exp_f32_e32 v158, v158
	v_add_f32_e32 v243, v157, v243
	s_waitcnt lgkmcnt(4)
	v_mfma_f32_32x32x16_bf16 v[200:215], v[220:223], v[236:239], v[200:215]
	v_exp_f32_e32 v159, v159
	v_add_f32_e32 v243, v158, v243
	v_add_f32_e32 v243, v159, v243
	v_add_f32_e32 v196, v196, v243
	s_waitcnt lgkmcnt(2)
	v_mfma_f32_32x32x16_bf16 v[200:215], v[224:227], v[244:247], v[200:215]
	v_cvt_pk_bf16_f32 v144, v144, v145
	v_cvt_pk_bf16_f32 v145, v146, v147
	v_cvt_pk_bf16_f32 v146, v148, v149
	v_cvt_pk_bf16_f32 v147, v150, v151
	s_waitcnt lgkmcnt(0)
	v_mfma_f32_32x32x16_bf16 v[200:215], v[228:231], v[248:251], v[200:215]
	ds_read_b128 v[216:219], v198 offset:64
	ds_read_b128 v[224:227], v198 offset:4672
	ds_read_b128 v[232:235], v198 offset:9280
	ds_read_b128 v[244:247], v198 offset:13888
	ds_read_b128 v[220:223], v198 offset:96
	ds_read_b128 v[228:231], v198 offset:4704
	ds_read_b128 v[236:239], v198 offset:9312
	ds_read_b128 v[248:251], v198 offset:13920
	v_cvt_pk_bf16_f32 v148, v152, v153
	v_cvt_pk_bf16_f32 v149, v154, v155
	v_cvt_pk_bf16_f32 v150, v156, v157
	v_cvt_pk_bf16_f32 v151, v158, v159
	s_waitcnt lgkmcnt(7)
	v_mfma_f32_32x32x16_bf16 v[112:127], v[216:219], v[144:147], v[112:127]
	v_exp_f32_e32 v200, v200
	v_exp_f32_e32 v201, v201
	v_exp_f32_e32 v202, v202
	v_add_f32_e32 v243, v200, v201
	v_exp_f32_e32 v203, v203
	s_waitcnt lgkmcnt(6)
	v_mfma_f32_32x32x16_bf16 v[80:95], v[224:227], v[144:147], v[80:95]
	v_add_f32_e32 v243, v202, v243
	v_exp_f32_e32 v204, v204
	v_add_f32_e32 v243, v203, v243
	v_exp_f32_e32 v205, v205
	v_add_f32_e32 v243, v204, v243
	s_waitcnt lgkmcnt(5)
	v_mfma_f32_32x32x16_bf16 v[48:63], v[232:235], v[144:147], v[48:63]
	v_exp_f32_e32 v206, v206
	v_add_f32_e32 v243, v205, v243
	v_exp_f32_e32 v207, v207
	v_add_f32_e32 v243, v206, v243
	v_exp_f32_e32 v208, v208
	s_waitcnt lgkmcnt(4)
	v_mfma_f32_32x32x16_bf16 v[16:31], v[244:247], v[144:147], v[16:31]
	v_add_f32_e32 v243, v207, v243
	v_exp_f32_e32 v209, v209
	v_add_f32_e32 v243, v208, v243
	v_exp_f32_e32 v210, v210
	v_add_f32_e32 v243, v209, v243
	s_waitcnt lgkmcnt(3)
	v_mfma_f32_32x32x16_bf16 v[112:127], v[220:223], v[148:151], v[112:127]
	v_exp_f32_e32 v211, v211
	v_add_f32_e32 v243, v210, v243
	v_exp_f32_e32 v212, v212
	v_add_f32_e32 v243, v211, v243
	v_exp_f32_e32 v213, v213
	s_waitcnt lgkmcnt(2)
	v_mfma_f32_32x32x16_bf16 v[80:95], v[228:231], v[148:151], v[80:95]
	v_add_f32_e32 v243, v212, v243
	v_exp_f32_e32 v214, v214
	v_add_f32_e32 v243, v213, v243
	v_exp_f32_e32 v215, v215
	v_add_f32_e32 v243, v214, v243
	s_waitcnt lgkmcnt(1)
	v_mfma_f32_32x32x16_bf16 v[48:63], v[236:239], v[148:151], v[48:63]
	v_add_f32_e32 v243, v215, v243
	v_add_f32_e32 v197, v197, v243
	v_cvt_pk_bf16_f32 v200, v200, v201
	v_cvt_pk_bf16_f32 v201, v202, v203
	v_cvt_pk_bf16_f32 v202, v204, v205
	s_waitcnt lgkmcnt(0)
	v_mfma_f32_32x32x16_bf16 v[16:31], v[248:251], v[148:151], v[16:31]
	v_cvt_pk_bf16_f32 v203, v206, v207
	v_cvt_pk_bf16_f32 v204, v208, v209
	v_cvt_pk_bf16_f32 v205, v210, v211
	v_cvt_pk_bf16_f32 v206, v212, v213
	v_cvt_pk_bf16_f32 v207, v214, v215
	s_add_i32 s6, s42, 1
	s_waitcnt vmcnt(0)
	s_cmp_eq_u32 s33, 0
	s_cbranch_scc0 .Lqt_s0_1
	v_add_u32_e32 v252, 0x9000, v190
	ds_write_b128 v189, v[160:163] offset:36864
	ds_write2_b64 v252, v[164:165], v[166:167] offset1:2
	ds_write_b128 v189, v[168:171] offset:46080
	v_add_u32_e32 v252, 0xb000, v190
	ds_write2_b64 v252, v[172:173], v[174:175] offset0:128 offset1:130
	s_branch .Lqt_pf_1

.Lab_B0:
	ds_read_b128 v[236:239], v193 offset:32
	ds_read_b128 v[224:227], v199 offset:64
	ds_read_b128 v[244:247], v193 offset:64
	ds_read_b128 v[228:231], v199 offset:96
	ds_read_b128 v[248:251], v193 offset:96
	s_waitcnt lgkmcnt(6)
	v_mfma_f32_32x32x16_bf16 v[144:159], v[252:255], v[208:211], v[0:15]
	s_waitcnt lgkmcnt(4)
	v_mfma_f32_32x32x16_bf16 v[144:159], v[212:215], v[236:239], v[144:159]
	s_waitcnt lgkmcnt(2)
	v_mfma_f32_32x32x16_bf16 v[144:159], v[224:227], v[244:247], v[144:159]
	s_waitcnt lgkmcnt(0)
	v_mfma_f32_32x32x16_bf16 v[144:159], v[228:231], v[248:251], v[144:159]
	ds_read_b128 v[216:219], v199 offset:9216
	ds_read_b128 v[232:235], v193 offset:36864
	ds_read_b128 v[220:223], v199 offset:9248
	ds_read_b128 v[236:239], v193 offset:36896
	ds_read_b128 v[224:227], v199 offset:9280
	ds_read_b128 v[244:247], v193 offset:36928
	ds_read_b128 v[228:231], v199 offset:9312
	ds_read_b128 v[248:251], v193 offset:36960
	s_nop 3
	v_exp_f32_e32 v144, v144
	v_exp_f32_e32 v145, v145
	v_exp_f32_e32 v146, v146
	v_add_f32_e32 v243, v144, v145
	v_exp_f32_e32 v147, v147
	v_add_f32_e32 v243, v146, v243
	v_exp_f32_e32 v148, v148
	v_add_f32_e32 v243, v147, v243
	v_exp_f32_e32 v149, v149
	v_add_f32_e32 v243, v148, v243
	v_exp_f32_e32 v150, v150
	v_add_f32_e32 v243, v149, v243
	v_exp_f32_e32 v151, v151
	v_add_f32_e32 v243, v150, v243
	v_exp_f32_e32 v152, v152
	v_add_f32_e32 v243, v151, v243
	v_exp_f32_e32 v153, v153
	v_add_f32_e32 v243, v152, v243
	v_exp_f32_e32 v154, v154
	v_add_f32_e32 v243, v153, v243
	v_exp_f32_e32 v155, v155
	v_add_f32_e32 v243, v154, v243
	v_exp_f32_e32 v156, v156
	v_add_f32_e32 v243, v155, v243
	s_waitcnt lgkmcnt(6)
	v_mfma_f32_32x32x16_bf16 v[200:215], v[216:219], v[232:235], v[0:15]
	v_exp_f32_e32 v157, v157
	v_add_f32_e32 v243, v156, v243
	v_exp_f32_e32 v158, v158
	v_add_f32_e32 v243, v157, v243
	s_waitcnt lgkmcnt(4)
	v_mfma_f32_32x32x16_bf16 v[200:215], v[220:223], v[236:239], v[200:215]
	v_exp_f32_e32 v159, v159
	v_add_f32_e32 v243, v158, v243
	v_add_f32_e32 v243, v159, v243
	v_add_f32_e32 v196, v196, v243
	s_waitcnt lgkmcnt(2)
	v_mfma_f32_32x32x16_bf16 v[200:215], v[224:227], v[244:247], v[200:215]
	v_cvt_pk_bf16_f32 v144, v144, v145
	v_cvt_pk_bf16_f32 v145, v146, v147
	v_cvt_pk_bf16_f32 v146, v148, v149
	v_cvt_pk_bf16_f32 v147, v150, v151
	s_waitcnt lgkmcnt(0)
	v_mfma_f32_32x32x16_bf16 v[200:215], v[228:231], v[248:251], v[200:215]
	ds_read_b128 v[216:219], v198 offset:0
	ds_read_b128 v[224:227], v198 offset:4608
	ds_read_b128 v[232:235], v198 offset:9216
	ds_read_b128 v[244:247], v198 offset:13824
	ds_read_b128 v[220:223], v198 offset:32
	ds_read_b128 v[228:231], v198 offset:4640
	ds_read_b128 v[236:239], v198 offset:9248
	ds_read_b128 v[248:251], v198 offset:13856
	v_cvt_pk_bf16_f32 v148, v152, v153
	v_cvt_pk_bf16_f32 v149, v154, v155
	v_cvt_pk_bf16_f32 v150, v156, v157
	v_cvt_pk_bf16_f32 v151, v158, v159
	s_waitcnt lgkmcnt(7)
	v_mfma_f32_32x32x16_bf16 v[112:127], v[216:219], v[144:147], v[112:127]
	v_exp_f32_e32 v200, v200
	v_exp_f32_e32 v201, v201
	v_exp_f32_e32 v202, v202
	s_waitcnt lgkmcnt(6)
	v_mfma_f32_32x32x16_bf16 v[80:95], v[224:227], v[144:147], v[80:95]
	v_add_f32_e32 v243, v200, v201
	v_exp_f32_e32 v203, v203
	v_add_f32_e32 v243, v202, v243
	s_waitcnt lgkmcnt(5)
	v_mfma_f32_32x32x16_bf16 v[48:63], v[232:235], v[144:147], v[48:63]
	v_exp_f32_e32 v204, v204
	v_add_f32_e32 v243, v203, v243
	v_exp_f32_e32 v205, v205
	s_waitcnt lgkmcnt(4)
	v_mfma_f32_32x32x16_bf16 v[16:31], v[244:247], v[144:147], v[16:31]
	v_add_f32_e32 v243, v204, v243
	v_exp_f32_e32 v206, v206
	v_add_f32_e32 v243, v205, v243
	s_waitcnt lgkmcnt(3)
	v_mfma_f32_32x32x16_bf16 v[112:127], v[220:223], v[148:151], v[112:127]
	v_exp_f32_e32 v207, v207
	v_add_f32_e32 v243, v206, v243
	v_exp_f32_e32 v208, v208
	s_waitcnt lgkmcnt(2)
	v_mfma_f32_32x32x16_bf16 v[80:95], v[228:231], v[148:151], v[80:95]
	v_add_f32_e32 v243, v207, v243
	v_cvt_pk_bf16_f32 v200, v200, v201
	v_cvt_pk_bf16_f32 v201, v202, v203
	s_waitcnt lgkmcnt(1)
	v_mfma_f32_32x32x16_bf16 v[48:63], v[236:239], v[148:151], v[48:63]
	v_cvt_pk_bf16_f32 v202, v204, v205
	v_cvt_pk_bf16_f32 v203, v206, v207
	v_exp_f32_e32 v209, v209
	s_waitcnt lgkmcnt(0)
	v_mfma_f32_32x32x16_bf16 v[16:31], v[248:251], v[148:151], v[16:31]
	v_add_f32_e32 v243, v208, v243
	v_exp_f32_e32 v210, v210
	v_add_f32_e32 v243, v209, v243
	v_mfma_f32_32x32x16_bf16 v[128:143], v[216:219], v[200:203], v[128:143]
	v_exp_f32_e32 v211, v211
	v_add_f32_e32 v243, v210, v243
	v_exp_f32_e32 v212, v212
	v_add_f32_e32 v243, v211, v243
	v_mfma_f32_32x32x16_bf16 v[96:111], v[224:227], v[200:203], v[96:111]
	v_exp_f32_e32 v213, v213
	v_add_f32_e32 v243, v212, v243
	v_exp_f32_e32 v214, v214
	v_add_f32_e32 v243, v213, v243
	v_mfma_f32_32x32x16_bf16 v[64:79], v[232:235], v[200:203], v[64:79]
	v_exp_f32_e32 v215, v215
	v_add_f32_e32 v243, v214, v243
	v_add_f32_e32 v243, v215, v243
	v_add_f32_e32 v197, v197, v243
	v_mfma_f32_32x32x16_bf16 v[32:47], v[244:247], v[200:203], v[32:47]
	v_cvt_pk_bf16_f32 v204, v208, v209
	v_cvt_pk_bf16_f32 v205, v210, v211
	v_cvt_pk_bf16_f32 v206, v212, v213
	v_cvt_pk_bf16_f32 v207, v214, v215
	ds_read_b128 v[252:255], v199 offset:4608
	ds_read_b128 v[208:211], v193
	ds_read_b128 v[212:215], v199 offset:4640
	v_mfma_f32_32x32x16_bf16 v[128:143], v[220:223], v[204:207], v[128:143]
	v_mfma_f32_32x32x16_bf16 v[96:111], v[228:231], v[204:207], v[96:111]
	v_mfma_f32_32x32x16_bf16 v[64:79], v[236:239], v[204:207], v[64:79]
	v_mfma_f32_32x32x16_bf16 v[32:47], v[248:251], v[204:207], v[32:47]
	ds_read_b128 v[236:239], v193 offset:32
	ds_read_b128 v[224:227], v199 offset:4672
	ds_read_b128 v[244:247], v193 offset:64
	ds_read_b128 v[228:231], v199 offset:4704
	ds_read_b128 v[248:251], v193 offset:96
	s_waitcnt lgkmcnt(6)
	v_mfma_f32_32x32x16_bf16 v[144:159], v[252:255], v[208:211], v[0:15]
	s_waitcnt lgkmcnt(4)
	v_mfma_f32_32x32x16_bf16 v[144:159], v[212:215], v[236:239], v[144:159]
	s_waitcnt lgkmcnt(2)
	v_mfma_f32_32x32x16_bf16 v[144:159], v[224:227], v[244:247], v[144:159]
	s_waitcnt lgkmcnt(0)
	v_mfma_f32_32x32x16_bf16 v[144:159], v[228:231], v[248:251], v[144:159]
	ds_read_b128 v[216:219], v199 offset:13824
	ds_read_b128 v[232:235], v193 offset:36864
	ds_read_b128 v[220:223], v199 offset:13856
	ds_read_b128 v[236:239], v193 offset:36896
	ds_read_b128 v[224:227], v199 offset:13888
	ds_read_b128 v[244:247], v193 offset:36928
	ds_read_b128 v[228:231], v199 offset:13920
	ds_read_b128 v[248:251], v193 offset:36960
	s_nop 3
	v_exp_f32_e32 v144, v144
	v_exp_f32_e32 v145, v145
	v_exp_f32_e32 v146, v146
	v_add_f32_e32 v243, v144, v145
	v_exp_f32_e32 v147, v147
	v_add_f32_e32 v243, v146, v243
	v_exp_f32_e32 v148, v148
	v_add_f32_e32 v243, v147, v243
	v_exp_f32_e32 v149, v149
	v_add_f32_e32 v243, v148, v243
	v_exp_f32_e32 v150, v150
	v_add_f32_e32 v243, v149, v243
	v_exp_f32_e32 v151, v151
	v_add_f32_e32 v243, v150, v243
	v_exp_f32_e32 v152, v152
	v_add_f32_e32 v243, v151, v243
	v_exp_f32_e32 v153, v153
	v_add_f32_e32 v243, v152, v243
	v_exp_f32_e32 v154, v154
	v_add_f32_e32 v243, v153, v243
	v_exp_f32_e32 v155, v155
	v_add_f32_e32 v243, v154, v243
	v_exp_f32_e32 v156, v156
	v_add_f32_e32 v243, v155, v243
	s_waitcnt lgkmcnt(6)
	v_mfma_f32_32x32x16_bf16 v[200:215], v[216:219], v[232:235], v[0:15]
	v_exp_f32_e32 v157, v157
	v_add_f32_e32 v243, v156, v243
	v_exp_f32_e32 v158, v158
	v_add_f32_e32 v243, v157, v243
	s_waitcnt lgkmcnt(4)
	v_mfma_f32_32x32x16_bf16 v[200:215], v[220:223], v[236:239], v[200:215]
	v_exp_f32_e32 v159, v159
	v_add_f32_e32 v243, v158, v243
	v_add_f32_e32 v243, v159, v243
	v_add_f32_e32 v196, v196, v243
	s_waitcnt lgkmcnt(2)
	v_mfma_f32_32x32x16_bf16 v[200:215], v[224:227], v[244:247], v[200:215]
	v_cvt_pk_bf16_f32 v144, v144, v145
	v_cvt_pk_bf16_f32 v145, v146, v147
	v_cvt_pk_bf16_f32 v146, v148, v149
	v_cvt_pk_bf16_f32 v147, v150, v151
	s_waitcnt lgkmcnt(0)
	v_mfma_f32_32x32x16_bf16 v[200:215], v[228:231], v[248:251], v[200:215]
	ds_read_b128 v[216:219], v198 offset:64
	ds_read_b128 v[224:227], v198 offset:4672
	ds_read_b128 v[232:235], v198 offset:9280
	ds_read_b128 v[244:247], v198 offset:13888
	ds_read_b128 v[220:223], v198 offset:96
	ds_read_b128 v[228:231], v198 offset:4704
	ds_read_b128 v[236:239], v198 offset:9312
	ds_read_b128 v[248:251], v198 offset:13920
	v_cvt_pk_bf16_f32 v148, v152, v153
	v_cvt_pk_bf16_f32 v149, v154, v155
	v_cvt_pk_bf16_f32 v150, v156, v157
	v_cvt_pk_bf16_f32 v151, v158, v159
	s_waitcnt lgkmcnt(7)
	v_mfma_f32_32x32x16_bf16 v[112:127], v[216:219], v[144:147], v[112:127]
	v_exp_f32_e32 v200, v200
	v_exp_f32_e32 v201, v201
	v_exp_f32_e32 v202, v202
	v_add_f32_e32 v243, v200, v201
	v_exp_f32_e32 v203, v203
	s_waitcnt lgkmcnt(6)
	v_mfma_f32_32x32x16_bf16 v[80:95], v[224:227], v[144:147], v[80:95]
	v_add_f32_e32 v243, v202, v243
	v_exp_f32_e32 v204, v204
	v_add_f32_e32 v243, v203, v243
	v_exp_f32_e32 v205, v205
	v_add_f32_e32 v243, v204, v243
	s_waitcnt lgkmcnt(5)
	v_mfma_f32_32x32x16_bf16 v[48:63], v[232:235], v[144:147], v[48:63]
	v_exp_f32_e32 v206, v206
	v_add_f32_e32 v243, v205, v243
	v_exp_f32_e32 v207, v207
	v_add_f32_e32 v243, v206, v243
	v_exp_f32_e32 v208, v208
	s_waitcnt lgkmcnt(4)
	v_mfma_f32_32x32x16_bf16 v[16:31], v[244:247], v[144:147], v[16:31]
	v_add_f32_e32 v243, v207, v243
	v_exp_f32_e32 v209, v209
	v_add_f32_e32 v243, v208, v243
	v_exp_f32_e32 v210, v210
	v_add_f32_e32 v243, v209, v243
	s_waitcnt lgkmcnt(3)
	v_mfma_f32_32x32x16_bf16 v[112:127], v[220:223], v[148:151], v[112:127]
	v_exp_f32_e32 v211, v211
	v_add_f32_e32 v243, v210, v243
	v_exp_f32_e32 v212, v212
	v_add_f32_e32 v243, v211, v243
	v_exp_f32_e32 v213, v213
	s_waitcnt lgkmcnt(2)
	v_mfma_f32_32x32x16_bf16 v[80:95], v[228:231], v[148:151], v[80:95]
	v_add_f32_e32 v243, v212, v243
	v_exp_f32_e32 v214, v214
	v_add_f32_e32 v243, v213, v243
	v_exp_f32_e32 v215, v215
	v_add_f32_e32 v243, v214, v243
	s_waitcnt lgkmcnt(1)
	v_mfma_f32_32x32x16_bf16 v[48:63], v[236:239], v[148:151], v[48:63]
	v_add_f32_e32 v243, v215, v243
	v_add_f32_e32 v197, v197, v243
	v_cvt_pk_bf16_f32 v200, v200, v201
	v_cvt_pk_bf16_f32 v201, v202, v203
	v_cvt_pk_bf16_f32 v202, v204, v205
	s_waitcnt lgkmcnt(0)
	v_mfma_f32_32x32x16_bf16 v[16:31], v[248:251], v[148:151], v[16:31]
	v_cvt_pk_bf16_f32 v203, v206, v207
	v_cvt_pk_bf16_f32 v204, v208, v209
	v_cvt_pk_bf16_f32 v205, v210, v211
	v_cvt_pk_bf16_f32 v206, v212, v213
	v_cvt_pk_bf16_f32 v207, v214, v215
	s_add_i32 s6, s42, 1
	s_waitcnt vmcnt(0)
	s_cmp_eq_u32 s33, 0
	s_cbranch_scc0 .Lqt_s0_2
	v_add_u32_e32 v252, 0x9000, v190
	ds_write_b128 v189, v[160:163] offset:36864
	ds_write2_b64 v252, v[164:165], v[166:167] offset1:2
	ds_write_b128 v189, v[168:171] offset:46080
	v_add_u32_e32 v252, 0xb000, v190
	ds_write2_b64 v252, v[172:173], v[174:175] offset0:128 offset1:130
	s_branch .Lqt_pf_2
